# v098 + P10 cross-token prefetch of sort keys (EIDX/GATE of token t+1 loaded before token t's output stores; sort waits vmcnt(12), h waited at first use)
# baseline (speedup 1.0000x reference)
; __device__ __forceinline__ float bf_lo(unsigned u) { return __uint_as_float(u << 16); }
; __device__ __forceinline__ float bf_hi(unsigned u) { return __uint_as_float(u & 0xffff0000u); }
; __global__ void __launch_bounds__(NT, 2) mk_fwd(Args args) {
;     ...
;         const float* fg = args.in[28];
;         for (int tok = gw; tok < MTOK; tok += NGW) {
;             const int b = tok >> 11;
;             f32x2 hf2[16];
; #pragma unroll
;             for (int j = 0; j < 4; ++j) { const u32x4 a = *(const u32x4*)(HB + (size_t)tok * DM + lane * 32 + j * 8);
; #pragma unroll
;                 for (int q = 0; q < 4; ++q) hf2[j * 4 + q] = (f32x2){bf_lo(a[q]), bf_hi(a[q])}; }
;             const int e0 = EIDX[(size_t)tok * 128 + lane], e1 = EIDX[(size_t)tok * 128 + 64 + lane];
;             const float g0 = GATE[(size_t)tok * 128 + lane], g1 = GATE[(size_t)tok * 128 + 64 + lane];
;             const bool hi32 = (lane & 32) != 0, hi16 = (lane & 16) != 0; const int l3 = (lane & 3) << 4;
.LBB0_883:
	s_cmp_lt_i32 s94, 11
	s_cselect_b64 s[2:3], -1, 0
	s_and_b64 s[0:1], s[2:3], s[0:1]
	s_and_b64 s[0:1], s[0:1], s[86:87]
	s_andn2_b64 vcc, exec, s[0:1]
	s_cbranch_vccnz .LBB0_913
	s_waitcnt vmcnt(0)
	v_mbcnt_hi_u32_b32 v3, -1, v169
	v_and_b32_e32 v5, 64, v3
	v_xor_b32_e32 v4, 32, v3
	v_add_u32_e32 v6, 64, v5
	v_cmp_lt_i32_e32 vcc, v4, v6
	v_mov_b32_e32 v137, 0
	v_and_b32_e32 v0, 32, v168
	v_cndmask_b32_e32 v4, v3, v4, vcc
	v_cmp_eq_u32_e64 s[0:1], 0, v0
	v_and_b32_e32 v0, 16, v168
	v_mov_b32_e32 v131, v137
	v_lshlrev_b32_e32 v129, 2, v4
	v_xor_b32_e32 v4, 16, v3
	v_cmp_eq_u32_e64 s[2:3], 0, v0
	v_lshlrev_b32_e32 v2, 4, v168
	v_lshl_add_u64 v[0:1], s[92:93], 0, v[130:131]
	s_mov_b64 s[4:5], 0x2a00000
	v_cmp_lt_i32_e32 vcc, v4, v6
	s_add_u32 s6, s92, 0x6a00000
	v_lshl_add_u64 v[96:97], s[80:81], 0, v[136:137]
	v_lshl_add_u64 v[98:99], v[0:1], 0, s[4:5]
	v_cndmask_b32_e32 v3, v3, v4, vcc
	v_and_or_b32 v2, v2, 48, v5
	s_mov_b64 s[4:5], 0x4a00000
	v_lshlrev_b32_e32 v136, 7, v128
	v_and_b32_e32 v148, 60, v128
	s_addc_u32 s7, s93, 0
	v_lshlrev_b32_e32 v146, 2, v3
	v_lshlrev_b32_e32 v147, 2, v2
	v_lshl_add_u64 v[100:101], v[0:1], 0, s[4:5]
	v_lshl_add_u64 v[102:103], s[90:91], 0, v[136:137]
	v_lshl_add_u64 v[104:105], s[88:89], 0, v[136:137]
	v_add_u32_e32 v149, -12, v148
	v_add_u32_e32 v150, -8, v148
	v_add_u32_e32 v151, -4, v148
	s_mov_b32 s11, 0x378e98ab
	s_mov_b32 s13, 0x3b7cd369
	s_mov_b32 s15, 0xbcc618b2
	s_mov_b32 s17, 0x3dda74e4
	s_mov_b32 s19, 0x3f228afd
	s_mov_b32 s21, 0x3e03c728
	s_mov_b32 s23, 0xbfb8aa3b
	s_mov_b32 s25, 0x42ce8ed0
	s_mov_b32 s26, 0xc2b17218
	v_mov_b32_e32 v152, 0x3ba10414
	s_brev_b32 s27, -2
	v_lshlrev_b32_e32 v136, 2, v138
	s_mov_b64 s[8:9], 0xa000
	s_mov_b32 s28, 0xa000
	v_mov_b32_e32 v153, 0x358637bd
	s_mov_b32 s29, 0x800000
	v_mov_b32_e32 v154, 0xb9c68948
	v_mov_b32_e32 v155, 0x7f800000
	s_mov_b32 s50, 0x55555555
	s_mov_b32 s51, 0x55555555
	s_mov_b32 s52, 0x33333333
	s_mov_b32 s53, 0x33333333
	s_mov_b32 s54, 0xf0f0f0f
	s_mov_b32 s55, 0xf0f0f0f
	s_mov_b32 s56, 0xff00ff
	s_mov_b32 s57, 0xff00ff
	s_mov_b32 s58, 0xffff
	s_mov_b32 s59, 0xffff
	s_mov_b32 s60, -1
	s_mov_b32 s61, 0
	global_load_dwordx4 v[186:189], v[104:105], off
	global_load_dwordx4 v[190:193], v[104:105], off offset:16
	global_load_dwordx4 v[194:197], v[104:105], off offset:32
	global_load_dwordx4 v[198:201], v[104:105], off offset:48
	global_load_dwordx4 v[202:205], v[104:105], off offset:64
	global_load_dwordx4 v[206:209], v[104:105], off offset:80
	global_load_dwordx4 v[210:213], v[104:105], off offset:96
	global_load_dwordx4 v[214:217], v[104:105], off offset:112
	s_min_i32 s4, s70, 0x3fff
	s_ashr_i32 s5, s4, 31
	s_lshl_b64 s[4:5], s[4:5], 9
	v_lshl_or_b32 v246, v128, 2, s4
	v_mov_b32_e32 v247, s5
	v_lshl_add_u64 v[184:185], s[46:47], 0, v[246:247]
	v_lshl_add_u64 v[246:247], s[48:49], 0, v[246:247]
	global_load_dword v242, v[184:185], off
	global_load_dword v243, v[184:185], off offset:256
	global_load_dword v244, v[246:247], off
	global_load_dword v245, v[246:247], off offset:256
	s_waitcnt vmcnt(0)
	s_branch .LBB0_886
.LBB0_885:
	s_ashr_i32 s10, s70, 11
	s_lshl_b64 s[4:5], s[70:71], 13
	v_lshl_add_u64 v[0:1], v[102:103], 0, s[4:5]
	s_mul_hi_i32 s5, s10, 0xc000
	s_mul_i32 s10, s10, 0xc000
	s_add_u32 s4, s74, s10
	s_addc_u32 s5, s75, s5
	v_lshl_add_u64 v[54:55], s[4:5], 0, v[136:137]
	v_lshl_add_u64 v[66:67], v[54:55], 0, s[8:9]
	global_load_dwordx4 v[2:5], v[0:1], off offset:48
	global_load_dwordx4 v[6:9], v[0:1], off offset:32
	global_load_dwordx4 v[10:13], v[0:1], off offset:16
	global_load_dwordx4 v[14:17], v[0:1], off
	global_load_dwordx4 v[18:21], v[66:67], off offset:32
	global_load_dwordx4 v[22:25], v[66:67], off offset:16
	global_load_dwordx4 v[26:29], v[66:67], off offset:48
	global_load_dwordx4 v[30:33], v[0:1], off offset:96
	global_load_dwordx4 v[34:37], v[0:1], off offset:80
	global_load_dwordx4 v[38:41], v[0:1], off offset:64
	global_load_dwordx4 v[42:45], v[66:67], off offset:64
	global_load_dwordx4 v[46:49], v[66:67], off offset:96
	global_load_dwordx4 v[50:53], v[66:67], off offset:80
	v_add_co_u32_e32 v68, vcc, s28, v54
	s_add_i32 s70, s70, s72
	s_nop 0
	v_addc_co_u32_e32 v69, vcc, 0, v55, vcc
	global_load_dwordx4 v[54:57], v[68:69], off
	global_load_dwordx4 v[58:61], v[0:1], off offset:112
	global_load_dwordx4 v[62:65], v[66:67], off offset:112
	s_min_i32 s4, s70, 0x3fff
	s_ashr_i32 s5, s4, 31
	s_lshl_b64 s[4:5], s[4:5], 9
	v_lshl_or_b32 v246, v128, 2, s4
	v_mov_b32_e32 v247, s5
	v_lshl_add_u64 v[184:185], s[46:47], 0, v[246:247]
	v_lshl_add_u64 v[246:247], s[48:49], 0, v[246:247]
	s_cmpk_gt_i32 s70, 0x3fff
	s_waitcnt vmcnt(11)
	v_pk_fma_f32 v[6:7], v[18:19], v[140:141], v[6:7]
	s_waitcnt vmcnt(10)
	v_pk_fma_f32 v[10:11], v[22:23], v[144:145], v[10:11]
	v_pk_fma_f32 v[12:13], v[24:25], v[142:143], v[12:13]
	v_pk_fma_f32 v[8:9], v[20:21], v[138:139], v[8:9]
	s_waitcnt vmcnt(9)
	v_pk_fma_f32 v[18:19], v[26:27], v[134:135], v[2:3]
	v_pk_fma_f32 v[20:21], v[28:29], v[132:133], v[4:5]
	s_waitcnt vmcnt(2)
; __device__ __forceinline__ float wave_sum(float v) { v = row16_sum(v); v += __shfl_xor(v, 16); v += __shfl_xor(v, 32); return v; }
; __global__ void __launch_bounds__(NT, 2) mk_fwd(Args args) {
;     ...
;             for (int q = 0; q < 8; ++q) { const f32x4 xv = *(const f32x4*)(xr + q * 4), g4 = *(const f32x4*)(gt2 + q * 4);
;                 float* a = acc + q * 4;
;                 a[0] = xv.x + g4.x * a[0]; a[1] = xv.y + g4.y * a[1]; a[2] = xv.z + g4.z * a[2]; a[3] = xv.w + g4.w * a[3];
;                 ss += (a[0] * a[0] + a[1] * a[1]) + (a[2] * a[2] + a[3] * a[3]); }
;             ss = wave_sum(ss);
;             const float rinv = rsqrtf(ss * (1.0f / DM) + 1e-6f);
; #pragma unroll
;             for (int q = 0; q < 8; ++q) { const f32x4 f4 = *(const f32x4*)(fg + lane * 32 + q * 4); const float* a = acc + q * 4;
;                 *(f32x4*)(xr + q * 4) = (f32x4){a[0] * rinv * f4.x, a[1] * rinv * f4.y, a[2] * rinv * f4.z, a[3] * rinv * f4.w}; }
	v_pk_fma_f32 v[2:3], v[54:55], v[118:119], v[14:15]
	v_pk_fma_f32 v[4:5], v[56:57], v[122:123], v[16:17]
	v_pk_fma_f32 v[28:29], v[52:53], v[120:121], v[36:37]
	v_mov_b32_e32 v17, v11
	v_mov_b32_e32 v37, v13
	v_mov_b32_e32 v16, v3
	v_mov_b32_e32 v36, v5
	v_pk_fma_f32 v[24:25], v[44:45], v[126:127], v[40:41]
	v_pk_fma_f32 v[26:27], v[50:51], v[124:125], v[34:35]
	v_mov_b32_e32 v15, v10
	v_mov_b32_e32 v35, v12
	v_mov_b32_e32 v40, v7
	v_mov_b32_e32 v41, v9
	v_mov_b32_e32 v14, v2
	v_mov_b32_e32 v34, v4
	v_pk_mul_f32 v[16:17], v[16:17], v[16:17]
	v_pk_mul_f32 v[36:37], v[36:37], v[36:37]
	v_pk_fma_f32 v[22:23], v[42:43], v[130:131], v[38:39]
	v_mov_b32_e32 v38, v6
	v_mov_b32_e32 v39, v8
	v_pk_mul_f32 v[40:41], v[40:41], v[40:41]
	v_pk_fma_f32 v[14:15], v[14:15], v[14:15], v[16:17]
	v_pk_fma_f32 v[16:17], v[34:35], v[34:35], v[36:37]
	v_mul_f32_e32 v42, v19, v19
	v_mul_f32_e32 v44, v21, v21
	v_pk_fma_f32 v[38:39], v[38:39], v[38:39], v[40:41]
	v_pk_add_f32 v[14:15], v[14:15], v[16:17]
	v_pk_fma_f32 v[30:31], v[46:47], v[116:117], v[30:31]
	v_pk_fma_f32 v[32:33], v[48:49], v[114:115], v[32:33]
	v_pk_mul_f32 v[46:47], v[22:23], v[22:23]
	v_pk_mul_f32 v[48:49], v[24:25], v[24:25]
	v_pk_fma_f32 v[42:43], v[18:19], v[18:19], v[42:43] op_sel_hi:[1,1,0]
	v_pk_fma_f32 v[44:45], v[20:21], v[20:21], v[44:45] op_sel_hi:[1,1,0]
	v_pk_add_f32 v[34:35], v[38:39], v[38:39] op_sel:[0,1] op_sel_hi:[1,0]
	v_pk_add_f32 v[14:15], v[14:15], v[14:15] op_sel:[0,1] op_sel_hi:[1,0]
	v_mov_b32_e32 v52, v27
	v_mov_b32_e32 v53, v29
	v_mov_b32_e32 v43, v48
	v_mov_b32_e32 v45, v49
	v_mov_b32_e32 v35, v47
	v_mov_b32_e32 v15, v46
	v_mov_b32_e32 v50, v26
	v_mov_b32_e32 v51, v28
	v_pk_mul_f32 v[52:53], v[52:53], v[52:53]
	v_pk_add_f32 v[36:37], v[42:43], v[44:45]
	v_pk_add_f32 v[14:15], v[14:15], v[34:35]
	v_mul_f32_e32 v54, v31, v31
	v_mul_f32_e32 v56, v33, v33
	s_waitcnt vmcnt(0)
	v_pk_fma_f32 v[58:59], v[62:63], v[112:113], v[58:59]
	v_pk_fma_f32 v[60:61], v[64:65], v[110:111], v[60:61]
	v_pk_fma_f32 v[40:41], v[50:51], v[50:51], v[52:53]
	v_pk_add_f32 v[14:15], v[14:15], v[36:37]
	v_pk_fma_f32 v[54:55], v[30:31], v[30:31], v[54:55] op_sel_hi:[1,1,0]
	v_pk_fma_f32 v[56:57], v[32:33], v[32:33], v[56:57] op_sel_hi:[1,1,0]
	v_pk_mul_f32 v[62:63], v[58:59], v[58:59]
	v_pk_mul_f32 v[64:65], v[60:61], v[60:61]
	v_pk_add_f32 v[38:39], v[40:41], v[40:41] op_sel:[0,1] op_sel_hi:[1,0]
	v_pk_add_f32 v[14:15], v[14:15], v[14:15] op_sel:[0,1] op_sel_hi:[1,0]
	v_mov_b32_e32 v55, v64
	v_mov_b32_e32 v39, v63
	v_mov_b32_e32 v15, v62
	v_mov_b32_e32 v57, v65
	v_pk_add_f32 v[14:15], v[14:15], v[38:39]
	v_pk_add_f32 v[16:17], v[54:55], v[56:57]
	s_nop 0
	v_pk_add_f32 v[14:15], v[14:15], v[16:17]
	s_nop 0
	v_add_f32_e32 v14, v14, v15
	s_nop 1
	v_add_f32_dpp v14, v14, v14 quad_perm:[1,0,3,2] row_mask:0xf bank_mask:0xf bound_ctrl:1
	s_nop 1
	v_add_f32_dpp v14, v14, v14 quad_perm:[2,3,0,1] row_mask:0xf bank_mask:0xf bound_ctrl:1
	s_nop 1
	v_add_f32_dpp v14, v14, v14 row_half_mirror row_mask:0xf bank_mask:0xf bound_ctrl:1
	s_nop 1
	v_add_f32_dpp v14, v14, v14 row_mirror row_mask:0xf bank_mask:0xf bound_ctrl:1
	ds_bpermute_b32 v15, v146, v14
	s_waitcnt lgkmcnt(0)
	v_add_f32_e32 v14, v14, v15
	ds_bpermute_b32 v15, v129, v14
	s_waitcnt lgkmcnt(0)
	v_add_f32_e32 v14, v14, v15
	v_fmamk_f32 v14, v14, 0x3a000000, v153
	v_mul_f32_e32 v15, 0x4b800000, v14
	v_cmp_gt_f32_e32 vcc, s29, v14
	s_nop 1
	v_cndmask_b32_e32 v14, v14, v15, vcc
	v_rsq_f32_e32 v14, v14
	s_nop 0
	v_mul_f32_e32 v15, 0x45800000, v14
	v_cndmask_b32_e32 v14, v14, v15, vcc
	v_pk_mul_f32 v[2:3], v[14:15], v[2:3] op_sel_hi:[0,1]
	v_pk_mul_f32 v[4:5], v[14:15], v[4:5] op_sel_hi:[0,1]
	v_pk_mul_f32 v[10:11], v[14:15], v[10:11] op_sel_hi:[0,1]
	v_pk_mul_f32 v[12:13], v[14:15], v[12:13] op_sel_hi:[0,1]
	v_pk_mul_f32 v[6:7], v[14:15], v[6:7] op_sel_hi:[0,1]
	v_pk_mul_f32 v[8:9], v[14:15], v[8:9] op_sel_hi:[0,1]
	v_pk_mul_f32 v[18:19], v[14:15], v[18:19] op_sel_hi:[0,1]
	v_pk_mul_f32 v[20:21], v[14:15], v[20:21] op_sel_hi:[0,1]
	v_pk_mul_f32 v[22:23], v[14:15], v[22:23] op_sel_hi:[0,1]
	v_pk_mul_f32 v[24:25], v[14:15], v[24:25] op_sel_hi:[0,1]
	v_pk_mul_f32 v[26:27], v[14:15], v[26:27] op_sel_hi:[0,1]
	v_pk_mul_f32 v[28:29], v[14:15], v[28:29] op_sel_hi:[0,1]
	v_pk_mul_f32 v[30:31], v[14:15], v[30:31] op_sel_hi:[0,1]
	v_pk_mul_f32 v[32:33], v[14:15], v[32:33] op_sel_hi:[0,1]
	v_pk_mul_f32 v[58:59], v[14:15], v[58:59] op_sel_hi:[0,1]
	v_pk_mul_f32 v[60:61], v[14:15], v[60:61] op_sel_hi:[0,1]
	v_pk_mul_f32 v[2:3], v[186:187], v[2:3]
	v_pk_mul_f32 v[4:5], v[188:189], v[4:5]
	global_load_dword v242, v[184:185], off
	global_load_dword v243, v[184:185], off offset:256
	global_load_dword v244, v[246:247], off
	global_load_dword v245, v[246:247], off offset:256
	global_store_dwordx4 v[0:1], v[2:5], off
	v_pk_mul_f32 v[10:11], v[190:191], v[10:11]
	v_pk_mul_f32 v[12:13], v[192:193], v[12:13]
	global_store_dwordx4 v[0:1], v[10:13], off offset:16
	v_pk_mul_f32 v[6:7], v[194:195], v[6:7]
	v_pk_mul_f32 v[8:9], v[196:197], v[8:9]
	global_store_dwordx4 v[0:1], v[6:9], off offset:32
	v_pk_mul_f32 v[18:19], v[198:199], v[18:19]
	v_pk_mul_f32 v[20:21], v[200:201], v[20:21]
	global_store_dwordx4 v[0:1], v[18:21], off offset:48
	v_pk_mul_f32 v[22:23], v[202:203], v[22:23]
	v_pk_mul_f32 v[24:25], v[204:205], v[24:25]
	global_store_dwordx4 v[0:1], v[22:25], off offset:64
	v_pk_mul_f32 v[26:27], v[206:207], v[26:27]
	v_pk_mul_f32 v[28:29], v[208:209], v[28:29]
	global_store_dwordx4 v[0:1], v[26:29], off offset:80
	v_pk_mul_f32 v[30:31], v[210:211], v[30:31]
	v_pk_mul_f32 v[32:33], v[212:213], v[32:33]
	global_store_dwordx4 v[0:1], v[30:33], off offset:96
	v_pk_mul_f32 v[58:59], v[214:215], v[58:59]
	v_pk_mul_f32 v[60:61], v[216:217], v[60:61]
	global_store_dwordx4 v[0:1], v[58:61], off offset:112
	s_cbranch_scc1 .LBB0_913
; __device__ __forceinline__ float bf_lo(unsigned u) { return __uint_as_float(u << 16); }
; __device__ __forceinline__ float bf_hi(unsigned u) { return __uint_as_float(u & 0xffff0000u); }
; __global__ void __launch_bounds__(NT, 2) mk_fwd(Args args) {
;     ...
;         for (int tok = gw; tok < MTOK; tok += NGW) {
;             const int b = tok >> 11;
;             f32x2 hf2[16];
; #pragma unroll
;             for (int j = 0; j < 4; ++j) { const u32x4 a = *(const u32x4*)(HB + (size_t)tok * DM + lane * 32 + j * 8);
; #pragma unroll
;                 for (int q = 0; q < 4; ++q) hf2[j * 4 + q] = (f32x2){bf_lo(a[q]), bf_hi(a[q])}; }
;             const int e0 = EIDX[(size_t)tok * 128 + lane], e1 = EIDX[(size_t)tok * 128 + 64 + lane];
;             const float g0 = GATE[(size_t)tok * 128 + lane], g1 = GATE[(size_t)tok * 128 + 64 + lane];
;             const bool hi32 = (lane & 32) != 0, hi16 = (lane & 16) != 0; const int l3 = (lane & 3) << 4;
.LBB0_886:
	s_ashr_i32 s71, s70, 31
	s_lshl_b64 s[4:5], s[70:71], 9
	v_lshl_or_b32 v0, v128, 2, s4
	v_mov_b32_e32 v1, s5
	v_lshl_add_u64 v[2:3], s[46:47], 0, v[0:1]
	s_lshl_b64 s[4:5], s[70:71], 12
	v_lshl_add_u64 v[2:3], v[96:97], 0, s[4:5]
	global_load_dwordx4 v[32:35], v[2:3], off offset:48
	global_load_dwordx4 v[36:39], v[2:3], off offset:32
	global_load_dwordx4 v[40:43], v[2:3], off offset:16
	global_load_dwordx4 v[44:47], v[2:3], off
	v_or_b32_e32 v2, 0x100, v0
	v_mov_b32_e32 v3, v1
	v_lshl_add_u64 v[0:1], s[48:49], 0, v[0:1]
	v_lshl_add_u64 v[4:5], s[46:47], 0, v[2:3]
	v_lshl_add_u64 v[2:3], s[48:49], 0, v[2:3]
	s_cmp_eq_u32 s84, 0x100
	s_cbranch_scc0 .Lp10_nobar
	s_barrier
.Lp10_nobar:
	s_waitcnt vmcnt(12)
	v_mov_b32_e32 v108, v242
	v_mov_b32_e32 v106, v243
	v_mov_b32_e32 v110, v244
	v_mov_b32_e32 v156, v245
	v_lshl_or_b32 v170, v108, 7, v128
	v_lshlrev_b32_e32 v171, 7, v106
	v_or_b32_e32 v174, 64, v128
	v_or_b32_e32 v171, v171, v174
	s_nop 0
	s_xnor_b64 s[62:63], s[50:51], s[52:53]
	s_nop 1
	v_min_u32_dpp v172, v170, v170 quad_perm:[1,0,3,2] row_mask:0xf bank_mask:0xf
	v_max_u32_dpp v173, v170, v170 quad_perm:[1,0,3,2] row_mask:0xf bank_mask:0xf
	v_min_u32_dpp v175, v171, v171 quad_perm:[1,0,3,2] row_mask:0xf bank_mask:0xf
	v_max_u32_dpp v176, v171, v171 quad_perm:[1,0,3,2] row_mask:0xf bank_mask:0xf
	v_cndmask_b32_e64 v170, v173, v172, s[62:63]
	v_cndmask_b32_e64 v171, v176, v175, s[62:63]
	s_xnor_b64 s[62:63], s[52:53], s[54:55]
	s_nop 1
	v_min_u32_dpp v172, v170, v170 quad_perm:[2,3,0,1] row_mask:0xf bank_mask:0xf
	v_max_u32_dpp v173, v170, v170 quad_perm:[2,3,0,1] row_mask:0xf bank_mask:0xf
	v_min_u32_dpp v175, v171, v171 quad_perm:[2,3,0,1] row_mask:0xf bank_mask:0xf
	v_max_u32_dpp v176, v171, v171 quad_perm:[2,3,0,1] row_mask:0xf bank_mask:0xf
	v_cndmask_b32_e64 v170, v173, v172, s[62:63]
	v_cndmask_b32_e64 v171, v176, v175, s[62:63]
	s_xnor_b64 s[62:63], s[50:51], s[54:55]
	s_nop 1
	v_min_u32_dpp v172, v170, v170 quad_perm:[1,0,3,2] row_mask:0xf bank_mask:0xf
	v_max_u32_dpp v173, v170, v170 quad_perm:[1,0,3,2] row_mask:0xf bank_mask:0xf
	v_min_u32_dpp v175, v171, v171 quad_perm:[1,0,3,2] row_mask:0xf bank_mask:0xf
	v_max_u32_dpp v176, v171, v171 quad_perm:[1,0,3,2] row_mask:0xf bank_mask:0xf
	v_cndmask_b32_e64 v170, v173, v172, s[62:63]
	v_cndmask_b32_e64 v171, v176, v175, s[62:63]
	s_xnor_b64 s[62:63], s[54:55], s[56:57]
	s_nop 1
	v_mov_b32_dpp v174, v170 row_half_mirror row_mask:0xf bank_mask:0xf
	v_mov_b32_dpp v177, v171 row_half_mirror row_mask:0xf bank_mask:0xf
	s_nop 0
	v_min_u32_dpp v172, v174, v170 quad_perm:[3,2,1,0] row_mask:0xf bank_mask:0xf
	v_max_u32_dpp v173, v174, v170 quad_perm:[3,2,1,0] row_mask:0xf bank_mask:0xf
	v_min_u32_dpp v175, v177, v171 quad_perm:[3,2,1,0] row_mask:0xf bank_mask:0xf
	v_max_u32_dpp v176, v177, v171 quad_perm:[3,2,1,0] row_mask:0xf bank_mask:0xf
	v_cndmask_b32_e64 v170, v173, v172, s[62:63]
	v_cndmask_b32_e64 v171, v176, v175, s[62:63]
	s_xnor_b64 s[62:63], s[52:53], s[56:57]
	s_nop 1
	v_min_u32_dpp v172, v170, v170 quad_perm:[2,3,0,1] row_mask:0xf bank_mask:0xf
	v_max_u32_dpp v173, v170, v170 quad_perm:[2,3,0,1] row_mask:0xf bank_mask:0xf
	v_min_u32_dpp v175, v171, v171 quad_perm:[2,3,0,1] row_mask:0xf bank_mask:0xf
	v_max_u32_dpp v176, v171, v171 quad_perm:[2,3,0,1] row_mask:0xf bank_mask:0xf
	v_cndmask_b32_e64 v170, v173, v172, s[62:63]
	v_cndmask_b32_e64 v171, v176, v175, s[62:63]
	s_xnor_b64 s[62:63], s[50:51], s[56:57]
	s_nop 1
	v_min_u32_dpp v172, v170, v170 quad_perm:[1,0,3,2] row_mask:0xf bank_mask:0xf
	v_max_u32_dpp v173, v170, v170 quad_perm:[1,0,3,2] row_mask:0xf bank_mask:0xf
	v_min_u32_dpp v175, v171, v171 quad_perm:[1,0,3,2] row_mask:0xf bank_mask:0xf
	v_max_u32_dpp v176, v171, v171 quad_perm:[1,0,3,2] row_mask:0xf bank_mask:0xf
	v_cndmask_b32_e64 v170, v173, v172, s[62:63]
	v_cndmask_b32_e64 v171, v176, v175, s[62:63]
	s_xnor_b64 s[62:63], s[56:57], s[58:59]
	s_nop 1
	v_min_u32_dpp v172, v170, v170 row_ror:8 row_mask:0xf bank_mask:0xf
	v_max_u32_dpp v173, v170, v170 row_ror:8 row_mask:0xf bank_mask:0xf
	v_min_u32_dpp v175, v171, v171 row_ror:8 row_mask:0xf bank_mask:0xf
	v_max_u32_dpp v176, v171, v171 row_ror:8 row_mask:0xf bank_mask:0xf
	v_cndmask_b32_e64 v170, v173, v172, s[62:63]
	v_cndmask_b32_e64 v171, v176, v175, s[62:63]
	s_xnor_b64 s[62:63], s[54:55], s[58:59]
	s_nop 1
	v_mov_b32_dpp v174, v170 row_half_mirror row_mask:0xf bank_mask:0xf
	v_mov_b32_dpp v177, v171 row_half_mirror row_mask:0xf bank_mask:0xf
	s_nop 0
	v_min_u32_dpp v172, v174, v170 quad_perm:[3,2,1,0] row_mask:0xf bank_mask:0xf
	v_max_u32_dpp v173, v174, v170 quad_perm:[3,2,1,0] row_mask:0xf bank_mask:0xf
	v_min_u32_dpp v175, v177, v171 quad_perm:[3,2,1,0] row_mask:0xf bank_mask:0xf
	v_max_u32_dpp v176, v177, v171 quad_perm:[3,2,1,0] row_mask:0xf bank_mask:0xf
	v_cndmask_b32_e64 v170, v173, v172, s[62:63]
	v_cndmask_b32_e64 v171, v176, v175, s[62:63]
	s_xnor_b64 s[62:63], s[52:53], s[58:59]
	s_nop 1
	v_min_u32_dpp v172, v170, v170 quad_perm:[2,3,0,1] row_mask:0xf bank_mask:0xf
	v_max_u32_dpp v173, v170, v170 quad_perm:[2,3,0,1] row_mask:0xf bank_mask:0xf
	v_min_u32_dpp v175, v171, v171 quad_perm:[2,3,0,1] row_mask:0xf bank_mask:0xf
	v_max_u32_dpp v176, v171, v171 quad_perm:[2,3,0,1] row_mask:0xf bank_mask:0xf
	v_cndmask_b32_e64 v170, v173, v172, s[62:63]
	v_cndmask_b32_e64 v171, v176, v175, s[62:63]
	s_xnor_b64 s[62:63], s[50:51], s[58:59]
	s_nop 1
	v_min_u32_dpp v172, v170, v170 quad_perm:[1,0,3,2] row_mask:0xf bank_mask:0xf
	v_max_u32_dpp v173, v170, v170 quad_perm:[1,0,3,2] row_mask:0xf bank_mask:0xf
	v_min_u32_dpp v175, v171, v171 quad_perm:[1,0,3,2] row_mask:0xf bank_mask:0xf
	v_max_u32_dpp v176, v171, v171 quad_perm:[1,0,3,2] row_mask:0xf bank_mask:0xf
	v_cndmask_b32_e64 v170, v173, v172, s[62:63]
	v_cndmask_b32_e64 v171, v176, v175, s[62:63]
	s_xnor_b64 s[62:63], s[58:59], s[60:61]
	ds_bpermute_b32 v174, v146, v170
	ds_bpermute_b32 v177, v146, v171
	s_waitcnt lgkmcnt(1)
; __global__ void __launch_bounds__(NT, 2) mk_fwd(Args args) {
;     ...
;             const int e0 = EIDX[(size_t)tok * 128 + lane], e1 = EIDX[(size_t)tok * 128 + 64 + lane];
;             const float g0 = GATE[(size_t)tok * 128 + lane], g1 = GATE[(size_t)tok * 128 + 64 + lane];
;             const bool hi32 = (lane & 32) != 0, hi16 = (lane & 16) != 0; const int l3 = (lane & 3) << 4;
	v_min_u32_e32 v172, v174, v170
	v_max_u32_e32 v173, v174, v170
	s_waitcnt lgkmcnt(0)
	v_min_u32_e32 v175, v177, v171
	v_max_u32_e32 v176, v177, v171
	v_cndmask_b32_e64 v170, v173, v172, s[62:63]
	v_cndmask_b32_e64 v171, v176, v175, s[62:63]
	s_xnor_b64 s[62:63], s[56:57], s[60:61]
	s_nop 1
	v_min_u32_dpp v172, v170, v170 row_ror:8 row_mask:0xf bank_mask:0xf
	v_max_u32_dpp v173, v170, v170 row_ror:8 row_mask:0xf bank_mask:0xf
	v_min_u32_dpp v175, v171, v171 row_ror:8 row_mask:0xf bank_mask:0xf
	v_max_u32_dpp v176, v171, v171 row_ror:8 row_mask:0xf bank_mask:0xf
	v_cndmask_b32_e64 v170, v173, v172, s[62:63]
	v_cndmask_b32_e64 v171, v176, v175, s[62:63]
	s_xnor_b64 s[62:63], s[54:55], s[60:61]
	s_nop 1
	v_mov_b32_dpp v174, v170 row_half_mirror row_mask:0xf bank_mask:0xf
	v_mov_b32_dpp v177, v171 row_half_mirror row_mask:0xf bank_mask:0xf
	s_nop 0
	v_min_u32_dpp v172, v174, v170 quad_perm:[3,2,1,0] row_mask:0xf bank_mask:0xf
	v_max_u32_dpp v173, v174, v170 quad_perm:[3,2,1,0] row_mask:0xf bank_mask:0xf
	v_min_u32_dpp v175, v177, v171 quad_perm:[3,2,1,0] row_mask:0xf bank_mask:0xf
	v_max_u32_dpp v176, v177, v171 quad_perm:[3,2,1,0] row_mask:0xf bank_mask:0xf
	v_cndmask_b32_e64 v170, v173, v172, s[62:63]
	v_cndmask_b32_e64 v171, v176, v175, s[62:63]
	s_xnor_b64 s[62:63], s[52:53], s[60:61]
	s_nop 1
	v_min_u32_dpp v172, v170, v170 quad_perm:[2,3,0,1] row_mask:0xf bank_mask:0xf
	v_max_u32_dpp v173, v170, v170 quad_perm:[2,3,0,1] row_mask:0xf bank_mask:0xf
	v_min_u32_dpp v175, v171, v171 quad_perm:[2,3,0,1] row_mask:0xf bank_mask:0xf
	v_max_u32_dpp v176, v171, v171 quad_perm:[2,3,0,1] row_mask:0xf bank_mask:0xf
	v_cndmask_b32_e64 v170, v173, v172, s[62:63]
	v_cndmask_b32_e64 v171, v176, v175, s[62:63]
	s_xnor_b64 s[62:63], s[50:51], s[60:61]
	s_nop 1
	v_min_u32_dpp v172, v170, v170 quad_perm:[1,0,3,2] row_mask:0xf bank_mask:0xf
	v_max_u32_dpp v173, v170, v170 quad_perm:[1,0,3,2] row_mask:0xf bank_mask:0xf
	v_min_u32_dpp v175, v171, v171 quad_perm:[1,0,3,2] row_mask:0xf bank_mask:0xf
	v_max_u32_dpp v176, v171, v171 quad_perm:[1,0,3,2] row_mask:0xf bank_mask:0xf
	v_cndmask_b32_e64 v170, v173, v172, s[62:63]
	v_cndmask_b32_e64 v171, v176, v175, s[62:63]
	ds_bpermute_b32 v174, v129, v170
	ds_bpermute_b32 v177, v129, v171
	s_waitcnt lgkmcnt(1)
	v_min_u32_e32 v172, v174, v170
	v_max_u32_e32 v173, v174, v170
	s_waitcnt lgkmcnt(0)
	v_min_u32_e32 v175, v177, v171
	v_max_u32_e32 v176, v177, v171
	v_cndmask_b32_e64 v170, v173, v172, s[60:61]
	v_cndmask_b32_e64 v171, v175, v176, s[60:61]
	ds_bpermute_b32 v174, v146, v170
	ds_bpermute_b32 v177, v146, v171
	s_waitcnt lgkmcnt(1)
	v_min_u32_e32 v172, v174, v170
	v_max_u32_e32 v173, v174, v170
	s_waitcnt lgkmcnt(0)
	v_min_u32_e32 v175, v177, v171
	v_max_u32_e32 v176, v177, v171
	v_cndmask_b32_e64 v170, v173, v172, s[58:59]
	v_cndmask_b32_e64 v171, v175, v176, s[58:59]
	s_nop 1
	v_min_u32_dpp v172, v170, v170 row_ror:8 row_mask:0xf bank_mask:0xf
	v_max_u32_dpp v173, v170, v170 row_ror:8 row_mask:0xf bank_mask:0xf
	v_min_u32_dpp v175, v171, v171 row_ror:8 row_mask:0xf bank_mask:0xf
	v_max_u32_dpp v176, v171, v171 row_ror:8 row_mask:0xf bank_mask:0xf
	v_cndmask_b32_e64 v170, v173, v172, s[56:57]
	v_cndmask_b32_e64 v171, v175, v176, s[56:57]
	s_nop 1
	v_mov_b32_dpp v174, v170 row_half_mirror row_mask:0xf bank_mask:0xf
	v_mov_b32_dpp v177, v171 row_half_mirror row_mask:0xf bank_mask:0xf
	s_nop 0
	v_min_u32_dpp v172, v174, v170 quad_perm:[3,2,1,0] row_mask:0xf bank_mask:0xf
	v_max_u32_dpp v173, v174, v170 quad_perm:[3,2,1,0] row_mask:0xf bank_mask:0xf
	v_min_u32_dpp v175, v177, v171 quad_perm:[3,2,1,0] row_mask:0xf bank_mask:0xf
	v_max_u32_dpp v176, v177, v171 quad_perm:[3,2,1,0] row_mask:0xf bank_mask:0xf
	v_cndmask_b32_e64 v170, v173, v172, s[54:55]
	v_cndmask_b32_e64 v171, v175, v176, s[54:55]
	s_nop 1
	v_min_u32_dpp v172, v170, v170 quad_perm:[2,3,0,1] row_mask:0xf bank_mask:0xf
	v_max_u32_dpp v173, v170, v170 quad_perm:[2,3,0,1] row_mask:0xf bank_mask:0xf
	v_min_u32_dpp v175, v171, v171 quad_perm:[2,3,0,1] row_mask:0xf bank_mask:0xf
	v_max_u32_dpp v176, v171, v171 quad_perm:[2,3,0,1] row_mask:0xf bank_mask:0xf
	v_cndmask_b32_e64 v170, v173, v172, s[52:53]
	v_cndmask_b32_e64 v171, v175, v176, s[52:53]
	s_nop 1
	v_min_u32_dpp v172, v170, v170 quad_perm:[1,0,3,2] row_mask:0xf bank_mask:0xf
	v_max_u32_dpp v173, v170, v170 quad_perm:[1,0,3,2] row_mask:0xf bank_mask:0xf
	v_min_u32_dpp v175, v171, v171 quad_perm:[1,0,3,2] row_mask:0xf bank_mask:0xf
	v_max_u32_dpp v176, v171, v171 quad_perm:[1,0,3,2] row_mask:0xf bank_mask:0xf
	v_cndmask_b32_e64 v170, v173, v172, s[50:51]
	v_cndmask_b32_e64 v171, v175, v176, s[50:51]
	v_min_u32_e32 v172, v170, v171
	v_max_u32_e32 v171, v170, v171
	v_mov_b32_e32 v170, v172
	ds_bpermute_b32 v174, v129, v170
	ds_bpermute_b32 v177, v129, v171
	s_waitcnt lgkmcnt(1)
	v_min_u32_e32 v172, v174, v170
	v_max_u32_e32 v173, v174, v170
	s_waitcnt lgkmcnt(0)
	v_min_u32_e32 v175, v177, v171
	v_max_u32_e32 v176, v177, v171
	v_cndmask_b32_e64 v170, v173, v172, s[60:61]
	v_cndmask_b32_e64 v171, v176, v175, s[60:61]
	ds_bpermute_b32 v174, v146, v170
	ds_bpermute_b32 v177, v146, v171
	s_waitcnt lgkmcnt(1)
	v_min_u32_e32 v172, v174, v170
	v_max_u32_e32 v173, v174, v170
	s_waitcnt lgkmcnt(0)
; __device__ __forceinline__ float bf_lo(unsigned u) { return __uint_as_float(u << 16); }
; __device__ __forceinline__ float bf_hi(unsigned u) { return __uint_as_float(u & 0xffff0000u); }
; __device__ __forceinline__ float gelu1(float x) { return 0.5f * x * (1.0f + erff(x * 0.70710678118654752f)); }
; #define PU_LOAD(BUF, EV, S0) do { _Pragma("unroll") for (int i = 0; i < 8; ++i) { const int row_ = __builtin_amdgcn_readlane(EV, (S0) + i); BUF[i & 3][i >> 2] = *(const u32x4*)(PU8 + (size_t)row_ * 1024 + lane * 16); } } while (0)
; __global__ void __launch_bounds__(NT, 2) mk_fwd(Args args) {
;     ...
;             for (int j = 0; j < 4; ++j) { const u32x4 a = *(const u32x4*)(HB + (size_t)tok * DM + lane * 32 + j * 8);
; #pragma unroll
;                 for (int q = 0; q < 4; ++q) hf2[j * 4 + q] = (f32x2){bf_lo(a[q]), bf_hi(a[q])}; }
;             const int e0 = EIDX[(size_t)tok * 128 + lane], e1 = EIDX[(size_t)tok * 128 + 64 + lane];
;             const float g0 = GATE[(size_t)tok * 128 + lane], g1 = GATE[(size_t)tok * 128 + 64 + lane];
;             const bool hi32 = (lane & 32) != 0, hi16 = (lane & 16) != 0; const int l3 = (lane & 3) << 4;
;     ...
;             float act0 = 0.f, act1 = 0.f;
;             u32x4 bA[4][2], bB[4][2];
; #pragma unroll
;             for (int hh = 0; hh < 2; ++hh) {
;                 const int ev = hh ? e1 : e0; const float gv = hh ? g1 : g0; float dv = 0.f;
;                 PU_LOAD(bA, ev, 0);
; #pragma unroll 1
;                 for (int s = 0; s < 64; s += 16) {
;                     PU_LOAD(bB, ev, s + 8);
;                     PU_DOT4(bA, 0, s); PU_DOT4(bA, 1, s + 4);
;                     if (s + 16 < 64) PU_LOAD(bA, ev, s + 16);
;                     PU_DOT4(bB, 0, s + 8); PU_DOT4(bB, 1, s + 12);
;                 }
;                 const float d = dv * SCL[ev];
;                 const float a = gelu1(d) * gv * SCL[16384 + ev];
	v_min_u32_e32 v175, v177, v171
	v_max_u32_e32 v176, v177, v171
	v_cndmask_b32_e64 v170, v173, v172, s[58:59]
	v_cndmask_b32_e64 v171, v176, v175, s[58:59]
	s_nop 1
	v_min_u32_dpp v172, v170, v170 row_ror:8 row_mask:0xf bank_mask:0xf
	v_max_u32_dpp v173, v170, v170 row_ror:8 row_mask:0xf bank_mask:0xf
	v_min_u32_dpp v175, v171, v171 row_ror:8 row_mask:0xf bank_mask:0xf
	v_max_u32_dpp v176, v171, v171 row_ror:8 row_mask:0xf bank_mask:0xf
	v_cndmask_b32_e64 v170, v173, v172, s[56:57]
	v_cndmask_b32_e64 v171, v176, v175, s[56:57]
	s_nop 1
	v_mov_b32_dpp v174, v170 row_half_mirror row_mask:0xf bank_mask:0xf
	v_mov_b32_dpp v177, v171 row_half_mirror row_mask:0xf bank_mask:0xf
	s_nop 0
	v_min_u32_dpp v172, v174, v170 quad_perm:[3,2,1,0] row_mask:0xf bank_mask:0xf
	v_max_u32_dpp v173, v174, v170 quad_perm:[3,2,1,0] row_mask:0xf bank_mask:0xf
	v_min_u32_dpp v175, v177, v171 quad_perm:[3,2,1,0] row_mask:0xf bank_mask:0xf
	v_max_u32_dpp v176, v177, v171 quad_perm:[3,2,1,0] row_mask:0xf bank_mask:0xf
	v_cndmask_b32_e64 v170, v173, v172, s[54:55]
	v_cndmask_b32_e64 v171, v176, v175, s[54:55]
	s_nop 1
	v_min_u32_dpp v172, v170, v170 quad_perm:[2,3,0,1] row_mask:0xf bank_mask:0xf
	v_max_u32_dpp v173, v170, v170 quad_perm:[2,3,0,1] row_mask:0xf bank_mask:0xf
	v_min_u32_dpp v175, v171, v171 quad_perm:[2,3,0,1] row_mask:0xf bank_mask:0xf
	v_max_u32_dpp v176, v171, v171 quad_perm:[2,3,0,1] row_mask:0xf bank_mask:0xf
	v_cndmask_b32_e64 v170, v173, v172, s[52:53]
	v_cndmask_b32_e64 v171, v176, v175, s[52:53]
	s_nop 1
	v_min_u32_dpp v172, v170, v170 quad_perm:[1,0,3,2] row_mask:0xf bank_mask:0xf
	v_max_u32_dpp v173, v170, v170 quad_perm:[1,0,3,2] row_mask:0xf bank_mask:0xf
	v_min_u32_dpp v175, v171, v171 quad_perm:[1,0,3,2] row_mask:0xf bank_mask:0xf
	v_max_u32_dpp v176, v171, v171 quad_perm:[1,0,3,2] row_mask:0xf bank_mask:0xf
	v_cndmask_b32_e64 v170, v173, v172, s[50:51]
	v_cndmask_b32_e64 v171, v176, v175, s[50:51]
	v_and_b32_e32 v172, 63, v170
	v_lshlrev_b32_e32 v172, 2, v172
	ds_bpermute_b32 v173, v172, v110
	ds_bpermute_b32 v174, v172, v156
	v_and_b32_e32 v175, 63, v171
	v_lshlrev_b32_e32 v175, 2, v175
	ds_bpermute_b32 v176, v175, v110
	ds_bpermute_b32 v177, v175, v156
	v_and_b32_e32 v172, 64, v170
	v_cmp_eq_u32_e32 vcc, 0, v172
	s_waitcnt lgkmcnt(2)
	v_lshrrev_b32_e32 v108, 7, v170
	v_cndmask_b32_e32 v178, v174, v173, vcc
	v_and_b32_e32 v175, 64, v171
	v_cmp_eq_u32_e32 vcc, 0, v175
	s_waitcnt lgkmcnt(0)
	v_lshrrev_b32_e32 v106, 7, v171
	v_cndmask_b32_e32 v179, v177, v176, vcc
	v_mov_b32_e32 v110, v178
	v_mov_b32_e32 v156, v179
	v_ashrrev_i32_e32 v181, 31, v108
	v_mov_b32_e32 v180, v108
	v_ashrrev_i32_e32 v183, 31, v106
	v_mov_b32_e32 v182, v106
	v_lshl_add_u64 v[180:181], v[180:181], 2, s[6:7]
	v_lshl_add_u64 v[182:183], v[182:183], 2, s[6:7]
	global_load_dword v218, v[180:181], off
	global_load_dword v219, v[182:183], off
	s_mov_b32 s10, 0
	v_mov_b32_e32 v107, 0
	s_waitcnt vmcnt(2)
	v_lshlrev_b32_e32 v88, 16, v32
	v_readlane_b32 s4, v108, 0
	v_readlane_b32 s30, v108, 1
	v_readlane_b32 s34, v108, 2
	v_readlane_b32 s36, v108, 3
	v_readlane_b32 s38, v108, 4
	v_readlane_b32 s40, v108, 5
	v_readlane_b32 s42, v108, 6
	v_readlane_b32 s44, v108, 7
	s_ashr_i32 s5, s4, 31
	s_ashr_i32 s31, s30, 31
	s_ashr_i32 s35, s34, 31
	s_ashr_i32 s37, s36, 31
	s_ashr_i32 s39, s38, 31
	s_ashr_i32 s41, s40, 31
	s_ashr_i32 s43, s42, 31
	s_ashr_i32 s45, s44, 31
	s_lshl_b64 s[4:5], s[4:5], 10
	s_lshl_b64 s[30:31], s[30:31], 10
	s_lshl_b64 s[34:35], s[34:35], 10
	s_lshl_b64 s[36:37], s[36:37], 10
	s_lshl_b64 s[38:39], s[38:39], 10
	s_lshl_b64 s[40:41], s[40:41], 10
	s_lshl_b64 s[42:43], s[42:43], 10
	s_lshl_b64 s[44:45], s[44:45], 10
	v_lshl_add_u64 v[48:49], v[98:99], 0, s[4:5]
	v_lshl_add_u64 v[50:51], v[98:99], 0, s[30:31]
	v_lshl_add_u64 v[52:53], v[98:99], 0, s[34:35]
	v_lshl_add_u64 v[54:55], v[98:99], 0, s[36:37]
	v_lshl_add_u64 v[56:57], v[98:99], 0, s[38:39]
	v_lshl_add_u64 v[58:59], v[98:99], 0, s[40:41]
	v_lshl_add_u64 v[60:61], v[98:99], 0, s[42:43]
	v_lshl_add_u64 v[62:63], v[98:99], 0, s[44:45]
	global_load_dwordx4 v[0:3], v[48:49], off
	global_load_dwordx4 v[4:7], v[50:51], off
	global_load_dwordx4 v[8:11], v[52:53], off
	global_load_dwordx4 v[12:15], v[54:55], off
	global_load_dwordx4 v[16:19], v[56:57], off
	global_load_dwordx4 v[20:23], v[58:59], off
	global_load_dwordx4 v[24:27], v[60:61], off
	global_load_dwordx4 v[28:31], v[62:63], off
	s_waitcnt vmcnt(11)
	v_lshlrev_b32_e32 v64, 16, v44
	v_and_b32_e32 v65, 0xffff0000, v44
	v_lshlrev_b32_e32 v66, 16, v45
	v_and_b32_e32 v67, 0xffff0000, v45
	v_lshlrev_b32_e32 v68, 16, v46
	v_and_b32_e32 v69, 0xffff0000, v46
	v_lshlrev_b32_e32 v70, 16, v47
	v_and_b32_e32 v71, 0xffff0000, v47
	v_lshlrev_b32_e32 v72, 16, v40
	v_and_b32_e32 v73, 0xffff0000, v40
	v_lshlrev_b32_e32 v74, 16, v41
	v_and_b32_e32 v75, 0xffff0000, v41
	v_lshlrev_b32_e32 v76, 16, v42
	v_and_b32_e32 v77, 0xffff0000, v42
	v_lshlrev_b32_e32 v78, 16, v43
	v_and_b32_e32 v79, 0xffff0000, v43
	v_lshlrev_b32_e32 v80, 16, v36
	v_and_b32_e32 v81, 0xffff0000, v36
	v_lshlrev_b32_e32 v82, 16, v37
	v_and_b32_e32 v83, 0xffff0000, v37
	v_lshlrev_b32_e32 v84, 16, v38
	v_and_b32_e32 v85, 0xffff0000, v38
	v_lshlrev_b32_e32 v86, 16, v39
	v_and_b32_e32 v87, 0xffff0000, v39
	v_and_b32_e32 v89, 0xffff0000, v32
	v_lshlrev_b32_e32 v90, 16, v33
	v_and_b32_e32 v91, 0xffff0000, v33
	v_lshlrev_b32_e32 v92, 16, v34
	v_and_b32_e32 v93, 0xffff0000, v34
	v_lshlrev_b32_e32 v94, 16, v35
	v_and_b32_e32 v95, 0xffff0000, v35
